# EpiRes accumulator init and epilogue: 192 v_pk_mul_f32 replaced by scalar v_mul_f32 pairs (same arithmetic)
# speedup vs baseline: 1.0119x; 1.0004x over previous
.LBB0_592:
	s_add_i32 m0, s68, 0x18000
	v_lshl_add_u64 v[64:65], v[64:65], 0, s[70:71]
	s_waitcnt vmcnt(4)
	s_barrier
	global_load_lds_dwordx4 v[64:65], off
	v_lshl_add_u64 v[64:65], v[66:67], 0, s[70:71]
	s_add_i32 m0, s68, 0x1a000
	s_add_i32 s79, s68, 0x8000
	global_load_lds_dwordx4 v[64:65], off
	v_lshl_add_u64 v[64:65], v[68:69], 0, s[70:71]
	s_mov_b32 m0, s79
	s_add_i32 s80, s68, 0xa000
	global_load_lds_dwordx4 v[64:65], off
	v_lshl_add_u64 v[64:65], v[70:71], 0, s[70:71]
	s_mov_b32 m0, s80
	v_or_b32_e32 v146, s7, v76
	global_load_lds_dwordx4 v[64:65], off
	s_add_i32 m0, s68, 0x1c000
	v_lshl_add_u64 v[64:65], v[72:73], 0, s[70:71]
	global_load_lds_dwordx4 v[64:65], off
	v_lshl_add_u64 v[64:65], v[74:75], 0, s[70:71]
	s_add_i32 m0, s68, 0x1e000
	v_lshlrev_b32_e32 v77, 4, v139
	global_load_lds_dwordx4 v[64:65], off
	v_lshlrev_b32_e32 v78, 6, v146
	s_movk_i32 s7, 0x3c0
	v_lshlrev_b32_e32 v79, 2, v146
	v_and_or_b32 v78, v78, s7, v77
	s_lshl_b32 s6, s6, 13
	v_and_b32_e32 v79, 32, v79
	v_lshl_or_b32 v77, v76, 6, v77
	v_lshlrev_b32_e32 v76, 2, v76
	v_bitop3_b32 v149, v78, s6, v79 bitop3:0xde
	s_lshl_b32 s6, s87, 12
	v_and_b32_e32 v76, 32, v76
	v_bitop3_b32 v147, v77, s6, v76 bitop3:0xde
	v_div_scale_f32 v66, s[6:7], s16, s16, 1.0
	v_rcp_f32_e32 v67, v66
	s_lshr_b32 s78, s17, 6
	s_add_i32 s81, s78, -2
	s_ashr_i32 s84, s39, 31
	v_fma_f32 v64, -v66, v67, 1.0
	v_fmac_f32_e32 v67, v64, v67
	v_div_scale_f32 v64, vcc, 1.0, s16, 1.0
	v_mul_f32_e32 v65, v64, v67
	v_fma_f32 v68, -v66, v65, v64
	v_fmac_f32_e32 v65, v68, v67
	v_fma_f32 v64, -v66, v65, v64
	v_div_fmas_f32 v64, v64, v67, v65
	v_div_fixup_f32 v136, v64, s16, 1.0
	s_waitcnt vmcnt(0)
	v_lshlrev_b32_e32 v64, 16, v62
	v_and_b32_e32 v65, 0xffff0000, v62
	v_mov_b32_e32 v137, v136
	v_lshlrev_b32_e32 v62, 16, v63
	v_and_b32_e32 v63, 0xffff0000, v63
	v_mul_f32_e32 v126, v136, v62
	v_mul_f32_e32 v127, v136, v63
	v_lshlrev_b32_e32 v62, 16, v60
	v_and_b32_e32 v63, 0xffff0000, v60
	v_lshlrev_b32_e32 v60, 16, v61
	v_and_b32_e32 v61, 0xffff0000, v61
	v_mul_f32_e32 v122, v136, v60
	v_mul_f32_e32 v123, v136, v61
	v_lshlrev_b32_e32 v60, 16, v58
	v_and_b32_e32 v61, 0xffff0000, v58
	v_lshlrev_b32_e32 v58, 16, v59
	v_and_b32_e32 v59, 0xffff0000, v59
	v_mul_f32_e32 v118, v136, v58
	v_mul_f32_e32 v119, v136, v59
	v_lshlrev_b32_e32 v58, 16, v56
	v_and_b32_e32 v59, 0xffff0000, v56
	v_lshlrev_b32_e32 v56, 16, v57
	v_and_b32_e32 v57, 0xffff0000, v57
	v_mul_f32_e32 v114, v136, v56
	v_mul_f32_e32 v115, v136, v57
	v_lshlrev_b32_e32 v56, 16, v54
	v_and_b32_e32 v57, 0xffff0000, v54
	v_lshlrev_b32_e32 v54, 16, v55
	v_and_b32_e32 v55, 0xffff0000, v55
	v_mul_f32_e32 v110, v136, v54
	v_mul_f32_e32 v111, v136, v55
	v_lshlrev_b32_e32 v54, 16, v52
	v_and_b32_e32 v55, 0xffff0000, v52
	v_lshlrev_b32_e32 v52, 16, v53
	v_and_b32_e32 v53, 0xffff0000, v53
	s_waitcnt lgkmcnt(0)
	v_mul_f32_e32 v106, v136, v52
	v_mul_f32_e32 v107, v136, v53
	v_lshlrev_b32_e32 v52, 16, v50
	v_and_b32_e32 v53, 0xffff0000, v50
	v_lshlrev_b32_e32 v50, 16, v51
	v_and_b32_e32 v51, 0xffff0000, v51
	v_mul_f32_e32 v102, v136, v50
	v_mul_f32_e32 v103, v136, v51
	v_lshlrev_b32_e32 v50, 16, v48
	v_and_b32_e32 v51, 0xffff0000, v48
	v_lshlrev_b32_e32 v48, 16, v49
	v_and_b32_e32 v49, 0xffff0000, v49
	v_mul_f32_e32 v98, v136, v48
	v_mul_f32_e32 v99, v136, v49
	v_lshlrev_b32_e32 v48, 16, v46
	v_and_b32_e32 v49, 0xffff0000, v46
	v_lshlrev_b32_e32 v46, 16, v47
	v_and_b32_e32 v47, 0xffff0000, v47
	v_mul_f32_e32 v94, v136, v46
	v_mul_f32_e32 v95, v136, v47
	v_lshlrev_b32_e32 v46, 16, v44
	v_and_b32_e32 v47, 0xffff0000, v44
	v_lshlrev_b32_e32 v44, 16, v45
	v_and_b32_e32 v45, 0xffff0000, v45
	v_mul_f32_e32 v90, v136, v44
	v_mul_f32_e32 v91, v136, v45
	v_lshlrev_b32_e32 v44, 16, v42
	v_and_b32_e32 v45, 0xffff0000, v42
	v_lshlrev_b32_e32 v42, 16, v43
	v_and_b32_e32 v43, 0xffff0000, v43
	v_mul_f32_e32 v86, v136, v42
	v_mul_f32_e32 v87, v136, v43
	v_lshlrev_b32_e32 v42, 16, v40
	v_and_b32_e32 v43, 0xffff0000, v40
	v_lshlrev_b32_e32 v40, 16, v41
	v_and_b32_e32 v41, 0xffff0000, v41
	v_mul_f32_e32 v82, v136, v40
	v_mul_f32_e32 v83, v136, v41
	v_lshlrev_b32_e32 v40, 16, v38
	v_and_b32_e32 v41, 0xffff0000, v38
	v_lshlrev_b32_e32 v38, 16, v39
	v_and_b32_e32 v39, 0xffff0000, v39
	v_mul_f32_e32 v78, v136, v38
	v_mul_f32_e32 v79, v136, v39
	v_lshlrev_b32_e32 v38, 16, v36
	v_and_b32_e32 v39, 0xffff0000, v36
	v_lshlrev_b32_e32 v36, 16, v37
	v_and_b32_e32 v37, 0xffff0000, v37
	v_mul_f32_e32 v74, v136, v36
	v_mul_f32_e32 v75, v136, v37
	v_lshlrev_b32_e32 v36, 16, v34
	v_and_b32_e32 v37, 0xffff0000, v34
	v_lshlrev_b32_e32 v34, 16, v35
	v_and_b32_e32 v35, 0xffff0000, v35
	v_mul_f32_e32 v70, v136, v34
	v_mul_f32_e32 v71, v136, v35
	v_lshlrev_b32_e32 v34, 16, v32
	v_and_b32_e32 v35, 0xffff0000, v32
	v_lshlrev_b32_e32 v32, 16, v33
	v_and_b32_e32 v33, 0xffff0000, v33
	v_mul_f32_e32 v66, v136, v32
	v_mul_f32_e32 v67, v136, v33
	v_lshlrev_b32_e32 v32, 16, v30
	v_and_b32_e32 v33, 0xffff0000, v30
	v_lshlrev_b32_e32 v30, 16, v31
	v_and_b32_e32 v31, 0xffff0000, v31
	v_mul_f32_e32 v120, v136, v62
	v_mul_f32_e32 v121, v136, v63
	v_mul_f32_e32 v62, v136, v30
	v_mul_f32_e32 v63, v136, v31
	v_lshlrev_b32_e32 v30, 16, v28
	v_and_b32_e32 v31, 0xffff0000, v28
	v_lshlrev_b32_e32 v28, 16, v29
	v_and_b32_e32 v29, 0xffff0000, v29
	v_mul_f32_e32 v112, v136, v58
	v_mul_f32_e32 v113, v136, v59
	v_mul_f32_e32 v58, v136, v28
	v_mul_f32_e32 v59, v136, v29
	v_lshlrev_b32_e32 v28, 16, v26
	v_and_b32_e32 v29, 0xffff0000, v26
	v_lshlrev_b32_e32 v26, 16, v27
	v_and_b32_e32 v27, 0xffff0000, v27
	v_mul_f32_e32 v104, v136, v54
	v_mul_f32_e32 v105, v136, v55
	v_mul_f32_e32 v54, v136, v26
	v_mul_f32_e32 v55, v136, v27
	v_lshlrev_b32_e32 v26, 16, v24
	v_and_b32_e32 v27, 0xffff0000, v24
	v_lshlrev_b32_e32 v24, 16, v25
	v_and_b32_e32 v25, 0xffff0000, v25
	v_mul_f32_e32 v96, v136, v50
	v_mul_f32_e32 v97, v136, v51
	v_mul_f32_e32 v50, v136, v24
	v_mul_f32_e32 v51, v136, v25
	v_lshlrev_b32_e32 v24, 16, v22
	v_and_b32_e32 v25, 0xffff0000, v22
	v_lshlrev_b32_e32 v22, 16, v23
	v_and_b32_e32 v23, 0xffff0000, v23
	v_mul_f32_e32 v88, v136, v46
	v_mul_f32_e32 v89, v136, v47
	v_mul_f32_e32 v46, v136, v22
	v_mul_f32_e32 v47, v136, v23
	v_lshlrev_b32_e32 v22, 16, v20
	v_and_b32_e32 v23, 0xffff0000, v20
	v_lshlrev_b32_e32 v20, 16, v21
	v_and_b32_e32 v21, 0xffff0000, v21
	v_mul_f32_e32 v80, v136, v42
	v_mul_f32_e32 v81, v136, v43
	v_mul_f32_e32 v42, v136, v20
	v_mul_f32_e32 v43, v136, v21
	v_lshlrev_b32_e32 v20, 16, v18
	v_and_b32_e32 v21, 0xffff0000, v18
	v_lshlrev_b32_e32 v18, 16, v19
	v_and_b32_e32 v19, 0xffff0000, v19
	v_mul_f32_e32 v72, v136, v38
	v_mul_f32_e32 v73, v136, v39
	v_mul_f32_e32 v38, v136, v18
	v_mul_f32_e32 v39, v136, v19
	v_lshlrev_b32_e32 v18, 16, v16
	v_and_b32_e32 v19, 0xffff0000, v16
	v_lshlrev_b32_e32 v16, 16, v17
	v_and_b32_e32 v17, 0xffff0000, v17
	v_mul_f32_e32 v124, v136, v64
	v_mul_f32_e32 v125, v136, v65
	v_mul_f32_e32 v64, v136, v34
	v_mul_f32_e32 v65, v136, v35
	v_mul_f32_e32 v34, v136, v16
	v_mul_f32_e32 v35, v136, v17
	v_lshlrev_b32_e32 v16, 16, v14
	v_and_b32_e32 v17, 0xffff0000, v14
	v_lshlrev_b32_e32 v14, 16, v15
	v_and_b32_e32 v15, 0xffff0000, v15
	v_mul_f32_e32 v108, v136, v56
	v_mul_f32_e32 v109, v136, v57
	v_mul_f32_e32 v56, v136, v30
	v_mul_f32_e32 v57, v136, v31
	v_mul_f32_e32 v30, v136, v14
	v_mul_f32_e32 v31, v136, v15
	v_lshlrev_b32_e32 v14, 16, v12
	v_and_b32_e32 v15, 0xffff0000, v12
	v_lshlrev_b32_e32 v12, 16, v13
	v_and_b32_e32 v13, 0xffff0000, v13
	v_mul_f32_e32 v92, v136, v48
	v_mul_f32_e32 v93, v136, v49
	v_mul_f32_e32 v48, v136, v26
	v_mul_f32_e32 v49, v136, v27
	v_mul_f32_e32 v26, v136, v12
	v_mul_f32_e32 v27, v136, v13
	v_lshlrev_b32_e32 v12, 16, v10
	v_and_b32_e32 v13, 0xffff0000, v10
	v_lshlrev_b32_e32 v10, 16, v11
	v_and_b32_e32 v11, 0xffff0000, v11
	v_mul_f32_e32 v76, v136, v40
	v_mul_f32_e32 v77, v136, v41
	v_mul_f32_e32 v40, v136, v22
	v_mul_f32_e32 v41, v136, v23
	v_mul_f32_e32 v22, v136, v10
	v_mul_f32_e32 v23, v136, v11
	v_lshlrev_b32_e32 v10, 16, v8
	v_and_b32_e32 v11, 0xffff0000, v8
	v_lshlrev_b32_e32 v8, 16, v9
	v_and_b32_e32 v9, 0xffff0000, v9
	v_mul_f32_e32 v116, v136, v60
	v_mul_f32_e32 v117, v136, v61
	v_mul_f32_e32 v60, v136, v32
	v_mul_f32_e32 v61, v136, v33
	v_mul_f32_e32 v32, v136, v18
	v_mul_f32_e32 v33, v136, v19
	v_mul_f32_e32 v18, v136, v8
	v_mul_f32_e32 v19, v136, v9
	v_lshlrev_b32_e32 v8, 16, v6
	v_and_b32_e32 v9, 0xffff0000, v6
	v_lshlrev_b32_e32 v6, 16, v7
	v_and_b32_e32 v7, 0xffff0000, v7
	v_mul_f32_e32 v84, v136, v44
	v_mul_f32_e32 v85, v136, v45
	v_mul_f32_e32 v44, v136, v24
	v_mul_f32_e32 v45, v136, v25
	v_mul_f32_e32 v24, v136, v14
	v_mul_f32_e32 v25, v136, v15
	v_mul_f32_e32 v14, v136, v6
	v_mul_f32_e32 v15, v136, v7
	v_lshlrev_b32_e32 v6, 16, v4
	v_and_b32_e32 v7, 0xffff0000, v4
	v_lshlrev_b32_e32 v4, 16, v5
	v_and_b32_e32 v5, 0xffff0000, v5
	v_add_u32_e32 v138, v141, v138
	s_waitcnt vmcnt(6)
	v_mul_f32_e32 v100, v136, v52
	v_mul_f32_e32 v101, v136, v53
	v_mul_f32_e32 v52, v136, v28
	v_mul_f32_e32 v53, v136, v29
	v_mul_f32_e32 v28, v136, v16
	v_mul_f32_e32 v29, v136, v17
	v_mul_f32_e32 v16, v136, v10
	v_mul_f32_e32 v17, v136, v11
	v_mul_f32_e32 v10, v136, v4
	v_mul_f32_e32 v11, v136, v5
	v_lshlrev_b32_e32 v4, 16, v0
	v_and_b32_e32 v5, 0xffff0000, v0
	v_lshlrev_b32_e32 v0, 16, v1
	v_and_b32_e32 v1, 0xffff0000, v1
	s_cmp_eq_u64 s[28:29], 0
	v_add_lshl_u32 v158, v138, v140, 1
	v_add_u32_e32 v140, v144, v142
	v_mul_f32_e32 v68, v136, v36
	v_mul_f32_e32 v69, v136, v37
	v_mul_f32_e32 v36, v136, v20
	v_mul_f32_e32 v37, v136, v21
	v_mul_f32_e32 v20, v136, v12
	v_mul_f32_e32 v21, v136, v13
	v_mul_f32_e32 v12, v136, v8
	v_mul_f32_e32 v13, v136, v9
	v_mul_f32_e32 v8, v136, v6
	v_mul_f32_e32 v9, v136, v7
	v_mul_f32_e32 v6, v136, v0
	v_mul_f32_e32 v7, v136, v1
	v_lshlrev_b32_e32 v0, 16, v2
	v_and_b32_e32 v1, 0xffff0000, v2
	v_lshlrev_b32_e32 v2, 16, v3
	v_and_b32_e32 v3, 0xffff0000, v3
	v_cmp_eq_u32_e64 s[6:7], 0, v139
	s_cselect_b64 s[20:21], -1, 0
	s_cmp_lg_u64 s[28:29], 0
	v_lshl_add_u64 v[138:139], s[22:23], 0, v[158:159]
	v_add_lshl_u32 v158, v140, v143, 1
	v_mul_f32_e32 v4, v136, v4
	v_mul_f32_e32 v5, v136, v5
	v_mul_f32_e32 v0, v136, v0
	v_mul_f32_e32 v1, v136, v1
	v_mul_f32_e32 v2, v136, v2
	v_mul_f32_e32 v3, v136, v3
	s_mov_b32 s43, 0
	s_mov_b32 s17, s16
	s_mov_b32 s18, s16
	s_mov_b32 s19, s16
	s_cselect_b64 s[58:59], -1, 0
	s_mov_b32 s31, s27
	s_and_b32 s29, s29, 0xffff
	s_and_b32 s25, s97, 0xffff
	s_mov_b32 s24, s96
	v_or_b32_e32 v148, s8, v145
	v_lshl_add_u64 v[140:141], s[22:23], 0, v[158:159]
	v_add_u32_e32 v149, 0, v149
	s_barrier
	s_branch .LBB0_594

.LBB0_605:
	s_add_i32 vcc_hi, s12, 2
	s_add_u32 s66, s10, 0x80
	s_addc_u32 s13, s11, 0
	s_add_i32 s2, 0, 0x10000
	v_add_u32_e32 v154, s2, v147
	ds_read_b128 v[142:145], v154
	ds_read_b128 v[150:153], v154 offset:1024
	ds_read_b128 v[166:169], v154 offset:2048
	ds_read_b128 v[170:173], v154 offset:3072
	s_cmp_eq_u32 s81, s12
	s_cselect_b32 s12, s62, s66
	s_cselect_b32 s13, s63, s13
	s_cselect_b32 s67, s75, vcc_lo
	s_cselect_b32 s66, s74, s73
	s_add_i32 m0, s68, 0xc000
	ds_read_b128 v[174:177], v149
	ds_read_b128 v[178:181], v149 offset:1024
	ds_read_b128 v[182:185], v149 offset:2048
	ds_read_b128 v[186:189], v149 offset:3072
	ds_read_b128 v[214:217], v149 offset:4096
	ds_read_b128 v[218:221], v149 offset:5120
	ds_read_b128 v[222:225], v149 offset:6144
	ds_read_b128 v[226:229], v149 offset:7168
	global_load_lds_dwordx4 v138, s[10:11]
	s_add_i32 m0, s68, 0xe000
	s_nop 0
	global_load_lds_dwordx4 v140, s[10:11]
	s_waitcnt lgkmcnt(8)
	s_barrier
	s_waitcnt lgkmcnt(0)
	s_setprio 1
	s_waitcnt lgkmcnt(0)
	v_mfma_f32_16x16x32_bf16 v[124:127], v[142:145], v[174:177], v[124:127]
	v_mfma_f32_16x16x32_bf16 v[120:123], v[166:169], v[174:177], v[120:123]
	v_mfma_f32_16x16x32_bf16 v[108:111], v[142:145], v[182:185], v[108:111]
	v_mfma_f32_16x16x32_bf16 v[104:107], v[166:169], v[182:185], v[104:107]
	v_mfma_f32_16x16x32_bf16 v[92:95], v[142:145], v[214:217], v[92:95]
	v_mfma_f32_16x16x32_bf16 v[88:91], v[166:169], v[214:217], v[88:91]
	v_mfma_f32_16x16x32_bf16 v[76:79], v[142:145], v[222:225], v[76:79]
	v_mfma_f32_16x16x32_bf16 v[72:75], v[166:169], v[222:225], v[72:75]
	v_mfma_f32_16x16x32_bf16 v[124:127], v[150:153], v[178:181], v[124:127]
	v_mfma_f32_16x16x32_bf16 v[120:123], v[170:173], v[178:181], v[120:123]
	v_mfma_f32_16x16x32_bf16 v[108:111], v[150:153], v[186:189], v[108:111]
	v_mfma_f32_16x16x32_bf16 v[104:107], v[170:173], v[186:189], v[104:107]
	v_mfma_f32_16x16x32_bf16 v[92:95], v[150:153], v[218:221], v[92:95]
	v_mfma_f32_16x16x32_bf16 v[88:91], v[170:173], v[218:221], v[88:91]
	v_mfma_f32_16x16x32_bf16 v[76:79], v[150:153], v[226:229], v[76:79]
	v_mfma_f32_16x16x32_bf16 v[72:75], v[170:173], v[226:229], v[72:75]
	s_setprio 0
	s_barrier
	s_add_i32 s15, 0, 0x14000
	v_add_u32_e32 v154, s15, v147
	s_add_i32 s2, s2, s0
	ds_read_b128 v[230:233], v154
	ds_read_b128 v[234:237], v154 offset:1024
	ds_read_b128 v[238:241], v154 offset:2048
	ds_read_b128 v[242:245], v154 offset:3072
	v_lshl_add_u64 v[154:155], s[66:67], 0, v[130:131]
	s_mov_b32 m0, s2
	v_lshl_add_u64 v[190:191], s[66:67], 0, v[134:135]
	global_load_lds_dwordx4 v130, s[66:67]
	s_add_i32 m0, s2, 0x2000
	s_nop 0
	global_load_lds_dwordx4 v134, s[66:67]
	s_barrier
	s_waitcnt lgkmcnt(0)
	s_setprio 1
	s_waitcnt lgkmcnt(0)
	v_mfma_f32_16x16x32_bf16 v[116:119], v[230:233], v[174:177], v[116:119]
	v_mfma_f32_16x16x32_bf16 v[112:115], v[238:241], v[174:177], v[112:115]
	v_mfma_f32_16x16x32_bf16 v[100:103], v[230:233], v[182:185], v[100:103]
	v_mfma_f32_16x16x32_bf16 v[96:99], v[238:241], v[182:185], v[96:99]
	v_mfma_f32_16x16x32_bf16 v[84:87], v[230:233], v[214:217], v[84:87]
	v_mfma_f32_16x16x32_bf16 v[80:83], v[238:241], v[214:217], v[80:83]
	v_mfma_f32_16x16x32_bf16 v[68:71], v[230:233], v[222:225], v[68:71]
	v_mfma_f32_16x16x32_bf16 v[64:67], v[238:241], v[222:225], v[64:67]
	v_mfma_f32_16x16x32_bf16 v[116:119], v[234:237], v[178:181], v[116:119]
	v_mfma_f32_16x16x32_bf16 v[112:115], v[242:245], v[178:181], v[112:115]
	v_mfma_f32_16x16x32_bf16 v[100:103], v[234:237], v[186:189], v[100:103]
	v_mfma_f32_16x16x32_bf16 v[96:99], v[242:245], v[186:189], v[96:99]
	v_mfma_f32_16x16x32_bf16 v[84:87], v[234:237], v[218:221], v[84:87]
	v_mfma_f32_16x16x32_bf16 v[80:83], v[242:245], v[218:221], v[80:83]
	v_mfma_f32_16x16x32_bf16 v[68:71], v[234:237], v[226:229], v[68:71]
	v_mfma_f32_16x16x32_bf16 v[64:67], v[242:245], v[226:229], v[64:67]
	s_setprio 0
	s_mov_b32 m0, s68
	v_lshl_add_u64 v[202:203], s[12:13], 0, v[128:129]
	s_barrier
	ds_read_b128 v[174:177], v149 offset:16384
	ds_read_b128 v[178:181], v149 offset:17408
	ds_read_b128 v[182:185], v149 offset:18432
	ds_read_b128 v[186:189], v149 offset:19456
	ds_read_b128 v[214:217], v149 offset:20480
	ds_read_b128 v[218:221], v149 offset:21504
	ds_read_b128 v[222:225], v149 offset:22528
	ds_read_b128 v[226:229], v149 offset:23552
	global_load_lds_dwordx4 v128, s[12:13]
	v_lshl_add_u64 v[204:205], s[12:13], 0, v[132:133]
	s_mov_b32 m0, s69
	s_nop 0
	global_load_lds_dwordx4 v132, s[12:13]
	s_barrier
	s_waitcnt lgkmcnt(0)
	s_setprio 1
	s_waitcnt lgkmcnt(0)
	v_mfma_f32_16x16x32_bf16 v[60:63], v[142:145], v[174:177], v[60:63]
	v_mfma_f32_16x16x32_bf16 v[56:59], v[166:169], v[174:177], v[56:59]
	v_mfma_f32_16x16x32_bf16 v[44:47], v[142:145], v[182:185], v[44:47]
	v_mfma_f32_16x16x32_bf16 v[40:43], v[166:169], v[182:185], v[40:43]
	v_mfma_f32_16x16x32_bf16 v[28:31], v[142:145], v[214:217], v[28:31]
	v_mfma_f32_16x16x32_bf16 v[24:27], v[166:169], v[214:217], v[24:27]
	v_mfma_f32_16x16x32_bf16 v[12:15], v[142:145], v[222:225], v[12:15]
	v_mfma_f32_16x16x32_bf16 v[8:11], v[166:169], v[222:225], v[8:11]
	v_mfma_f32_16x16x32_bf16 v[60:63], v[150:153], v[178:181], v[60:63]
	v_mfma_f32_16x16x32_bf16 v[56:59], v[170:173], v[178:181], v[56:59]
	v_mfma_f32_16x16x32_bf16 v[44:47], v[150:153], v[186:189], v[44:47]
	v_mfma_f32_16x16x32_bf16 v[40:43], v[170:173], v[186:189], v[40:43]
	v_mfma_f32_16x16x32_bf16 v[28:31], v[150:153], v[218:221], v[28:31]
	v_mfma_f32_16x16x32_bf16 v[24:27], v[170:173], v[218:221], v[24:27]
	v_mfma_f32_16x16x32_bf16 v[12:15], v[150:153], v[226:229], v[12:15]
	v_mfma_f32_16x16x32_bf16 v[8:11], v[170:173], v[226:229], v[8:11]
	s_setprio 0
	s_barrier
	s_add_u32 s66, s66, s35
	s_addc_u32 s67, s67, 0
	s_add_i32 s2, s15, s0
	v_lshl_add_u64 v[246:247], s[66:67], 0, v[130:131]
	s_mov_b32 m0, s2
	v_lshl_add_u64 v[248:249], s[66:67], 0, v[134:135]
	global_load_lds_dwordx4 v130, s[66:67]
	s_add_i32 m0, s2, 0x2000
	s_nop 0
	global_load_lds_dwordx4 v134, s[66:67]
	s_waitcnt vmcnt(6)
	s_barrier
	s_setprio 1
	v_mfma_f32_16x16x32_bf16 v[52:55], v[230:233], v[174:177], v[52:55]
	v_mfma_f32_16x16x32_bf16 v[48:51], v[238:241], v[174:177], v[48:51]
	v_mfma_f32_16x16x32_bf16 v[36:39], v[230:233], v[182:185], v[36:39]
	v_mfma_f32_16x16x32_bf16 v[32:35], v[238:241], v[182:185], v[32:35]
	v_mfma_f32_16x16x32_bf16 v[20:23], v[230:233], v[214:217], v[20:23]
	v_mfma_f32_16x16x32_bf16 v[16:19], v[238:241], v[214:217], v[16:19]
	v_mfma_f32_16x16x32_bf16 v[4:7], v[230:233], v[222:225], v[4:7]
	v_mfma_f32_16x16x32_bf16 v[0:3], v[238:241], v[222:225], v[0:3]
	v_mfma_f32_16x16x32_bf16 v[52:55], v[234:237], v[178:181], v[52:55]
	v_mfma_f32_16x16x32_bf16 v[48:51], v[242:245], v[178:181], v[48:51]
	v_mfma_f32_16x16x32_bf16 v[36:39], v[234:237], v[186:189], v[36:39]
	v_mfma_f32_16x16x32_bf16 v[32:35], v[242:245], v[186:189], v[32:35]
	v_mfma_f32_16x16x32_bf16 v[20:23], v[234:237], v[218:221], v[20:23]
	v_mfma_f32_16x16x32_bf16 v[16:19], v[242:245], v[218:221], v[16:19]
	v_mfma_f32_16x16x32_bf16 v[4:7], v[234:237], v[226:229], v[4:7]
	v_mfma_f32_16x16x32_bf16 v[0:3], v[242:245], v[226:229], v[0:3]
	s_setprio 0
	s_add_i32 s2, 0, 0x18000
	v_add_u32_e32 v158, s2, v147
	s_barrier
	ds_read_b128 v[142:145], v158
	ds_read_b128 v[150:153], v158 offset:1024
	ds_read_b128 v[166:169], v158 offset:2048
	ds_read_b128 v[170:173], v158 offset:3072
	s_add_u32 s12, s12, s22
	s_addc_u32 s13, s13, 0
	s_mov_b32 m0, s76
	ds_read_b128 v[174:177], v149 offset:32768
	ds_read_b128 v[178:181], v149 offset:33792
	ds_read_b128 v[182:185], v149 offset:34816
	ds_read_b128 v[186:189], v149 offset:35840
	ds_read_b128 v[214:217], v149 offset:36864
	ds_read_b128 v[218:221], v149 offset:37888
	ds_read_b128 v[222:225], v149 offset:38912
	ds_read_b128 v[226:229], v149 offset:39936
	global_load_lds_dwordx4 v128, s[12:13]
	s_mov_b32 m0, s77
	s_nop 0
	global_load_lds_dwordx4 v132, s[12:13]
	s_waitcnt lgkmcnt(8)
	s_barrier
	s_waitcnt lgkmcnt(0)
	s_setprio 1
	s_waitcnt lgkmcnt(0)
	v_mfma_f32_16x16x32_bf16 v[124:127], v[142:145], v[174:177], v[124:127]
	v_mfma_f32_16x16x32_bf16 v[120:123], v[166:169], v[174:177], v[120:123]
	v_mfma_f32_16x16x32_bf16 v[108:111], v[142:145], v[182:185], v[108:111]
	v_mfma_f32_16x16x32_bf16 v[104:107], v[166:169], v[182:185], v[104:107]
	v_mfma_f32_16x16x32_bf16 v[92:95], v[142:145], v[214:217], v[92:95]
	v_mfma_f32_16x16x32_bf16 v[88:91], v[166:169], v[214:217], v[88:91]
	v_mfma_f32_16x16x32_bf16 v[76:79], v[142:145], v[222:225], v[76:79]
	v_mfma_f32_16x16x32_bf16 v[72:75], v[166:169], v[222:225], v[72:75]
	v_mfma_f32_16x16x32_bf16 v[124:127], v[150:153], v[178:181], v[124:127]
	v_mfma_f32_16x16x32_bf16 v[120:123], v[170:173], v[178:181], v[120:123]
	v_mfma_f32_16x16x32_bf16 v[108:111], v[150:153], v[186:189], v[108:111]
	v_mfma_f32_16x16x32_bf16 v[104:107], v[170:173], v[186:189], v[104:107]
	v_mfma_f32_16x16x32_bf16 v[92:95], v[150:153], v[218:221], v[92:95]
	v_mfma_f32_16x16x32_bf16 v[88:91], v[170:173], v[218:221], v[88:91]
	v_mfma_f32_16x16x32_bf16 v[76:79], v[150:153], v[226:229], v[76:79]
	v_mfma_f32_16x16x32_bf16 v[72:75], v[170:173], v[226:229], v[72:75]
	s_setprio 0
	s_barrier
	s_add_i32 s12, 0, 0x1c000
	s_add_i32 s2, s2, s0
	v_add_u32_e32 v158, s12, v147
	v_lshl_add_u64 v[154:155], v[154:155], 0, s[70:71]
	s_mov_b32 m0, s2
	ds_read_b128 v[230:233], v158
	ds_read_b128 v[234:237], v158 offset:1024
	ds_read_b128 v[238:241], v158 offset:2048
	ds_read_b128 v[242:245], v158 offset:3072
	global_load_lds_dwordx4 v[154:155], off
	v_lshl_add_u64 v[154:155], v[190:191], 0, s[70:71]
	s_add_i32 m0, s2, 0x2000
	s_nop 0
	global_load_lds_dwordx4 v[154:155], off
	s_barrier
	s_waitcnt lgkmcnt(0)
	s_setprio 1
	s_waitcnt lgkmcnt(0)
	v_mfma_f32_16x16x32_bf16 v[116:119], v[230:233], v[174:177], v[116:119]
	v_mfma_f32_16x16x32_bf16 v[112:115], v[238:241], v[174:177], v[112:115]
	v_mfma_f32_16x16x32_bf16 v[100:103], v[230:233], v[182:185], v[100:103]
	v_mfma_f32_16x16x32_bf16 v[96:99], v[238:241], v[182:185], v[96:99]
	v_mfma_f32_16x16x32_bf16 v[84:87], v[230:233], v[214:217], v[84:87]
	v_mfma_f32_16x16x32_bf16 v[80:83], v[238:241], v[214:217], v[80:83]
	v_mfma_f32_16x16x32_bf16 v[68:71], v[230:233], v[222:225], v[68:71]
	v_mfma_f32_16x16x32_bf16 v[64:67], v[238:241], v[222:225], v[64:67]
	v_mfma_f32_16x16x32_bf16 v[116:119], v[234:237], v[178:181], v[116:119]
	v_mfma_f32_16x16x32_bf16 v[112:115], v[242:245], v[178:181], v[112:115]
	v_mfma_f32_16x16x32_bf16 v[100:103], v[234:237], v[186:189], v[100:103]
	v_mfma_f32_16x16x32_bf16 v[96:99], v[242:245], v[186:189], v[96:99]
	v_mfma_f32_16x16x32_bf16 v[84:87], v[234:237], v[218:221], v[84:87]
	v_mfma_f32_16x16x32_bf16 v[80:83], v[242:245], v[218:221], v[80:83]
	v_mfma_f32_16x16x32_bf16 v[68:71], v[234:237], v[226:229], v[68:71]
	v_mfma_f32_16x16x32_bf16 v[64:67], v[242:245], v[226:229], v[64:67]
	s_setprio 0
	s_mov_b32 m0, s79
	v_lshl_add_u64 v[154:155], v[202:203], 0, s[70:71]
	s_barrier
	ds_read_b128 v[174:177], v149 offset:49152
	ds_read_b128 v[178:181], v149 offset:50176
	ds_read_b128 v[182:185], v149 offset:51200
	ds_read_b128 v[186:189], v149 offset:52224
	ds_read_b128 v[214:217], v149 offset:53248
	ds_read_b128 v[218:221], v149 offset:54272
	ds_read_b128 v[222:225], v149 offset:55296
	ds_read_b128 v[226:229], v149 offset:56320
	global_load_lds_dwordx4 v[154:155], off
	v_lshl_add_u64 v[154:155], v[204:205], 0, s[70:71]
	s_mov_b32 m0, s80
	s_nop 0
	global_load_lds_dwordx4 v[154:155], off
	s_barrier
	s_waitcnt lgkmcnt(0)
	s_setprio 1
	s_waitcnt lgkmcnt(0)
	v_mfma_f32_16x16x32_bf16 v[60:63], v[142:145], v[174:177], v[60:63]
	v_mfma_f32_16x16x32_bf16 v[56:59], v[166:169], v[174:177], v[56:59]
	v_mfma_f32_16x16x32_bf16 v[44:47], v[142:145], v[182:185], v[44:47]
	v_mfma_f32_16x16x32_bf16 v[40:43], v[166:169], v[182:185], v[40:43]
	v_mfma_f32_16x16x32_bf16 v[28:31], v[142:145], v[214:217], v[28:31]
	v_mfma_f32_16x16x32_bf16 v[24:27], v[166:169], v[214:217], v[24:27]
	v_mfma_f32_16x16x32_bf16 v[12:15], v[142:145], v[222:225], v[12:15]
	v_mfma_f32_16x16x32_bf16 v[8:11], v[166:169], v[222:225], v[8:11]
	v_mfma_f32_16x16x32_bf16 v[60:63], v[150:153], v[178:181], v[60:63]
	v_mfma_f32_16x16x32_bf16 v[56:59], v[170:173], v[178:181], v[56:59]
	v_mfma_f32_16x16x32_bf16 v[44:47], v[150:153], v[186:189], v[44:47]
	v_mfma_f32_16x16x32_bf16 v[40:43], v[170:173], v[186:189], v[40:43]
	v_mfma_f32_16x16x32_bf16 v[28:31], v[150:153], v[218:221], v[28:31]
	v_mfma_f32_16x16x32_bf16 v[24:27], v[170:173], v[218:221], v[24:27]
	v_mfma_f32_16x16x32_bf16 v[12:15], v[150:153], v[226:229], v[12:15]
	v_mfma_f32_16x16x32_bf16 v[8:11], v[170:173], v[226:229], v[8:11]
	s_setprio 0
	s_barrier
	s_add_i32 s2, s12, s0
	v_lshl_add_u64 v[142:143], v[246:247], 0, s[70:71]
	s_mov_b32 m0, s2
	s_nop 0
	global_load_lds_dwordx4 v[142:143], off
	v_lshl_add_u64 v[142:143], v[248:249], 0, s[70:71]
	s_add_i32 m0, s2, 0x2000
	s_nop 0
	global_load_lds_dwordx4 v[142:143], off
	s_waitcnt vmcnt(6)
	s_barrier
	s_setprio 1
	v_mfma_f32_16x16x32_bf16 v[52:55], v[230:233], v[174:177], v[52:55]
	v_mfma_f32_16x16x32_bf16 v[48:51], v[238:241], v[174:177], v[48:51]
	v_mfma_f32_16x16x32_bf16 v[36:39], v[230:233], v[182:185], v[36:39]
	v_mfma_f32_16x16x32_bf16 v[32:35], v[238:241], v[182:185], v[32:35]
	v_mfma_f32_16x16x32_bf16 v[20:23], v[230:233], v[214:217], v[20:23]
	v_mfma_f32_16x16x32_bf16 v[16:19], v[238:241], v[214:217], v[16:19]
	v_mfma_f32_16x16x32_bf16 v[4:7], v[230:233], v[222:225], v[4:7]
	v_mfma_f32_16x16x32_bf16 v[0:3], v[238:241], v[222:225], v[0:3]
	v_mfma_f32_16x16x32_bf16 v[52:55], v[234:237], v[178:181], v[52:55]
	v_mfma_f32_16x16x32_bf16 v[48:51], v[242:245], v[178:181], v[48:51]
	v_mfma_f32_16x16x32_bf16 v[36:39], v[234:237], v[186:189], v[36:39]
	v_mfma_f32_16x16x32_bf16 v[32:35], v[242:245], v[186:189], v[32:35]
	v_mfma_f32_16x16x32_bf16 v[20:23], v[234:237], v[218:221], v[20:23]
	v_mfma_f32_16x16x32_bf16 v[16:19], v[242:245], v[218:221], v[16:19]
	v_mfma_f32_16x16x32_bf16 v[4:7], v[234:237], v[226:229], v[4:7]
	v_mfma_f32_16x16x32_bf16 v[0:3], v[242:245], v[226:229], v[0:3]
	s_setprio 0
	s_add_u32 s10, s10, 0x100
	s_addc_u32 s11, s11, 0
	s_add_u32 s73, s73, 0x100
	s_addc_u32 vcc_lo, vcc_lo, 0
	s_cmp_ge_u32 vcc_hi, s78
	s_mov_b32 s12, vcc_hi
	s_barrier
	s_cbranch_scc0 .LBB0_605
	v_lshl_add_u32 v142, s72, 8, v146
	v_ashrrev_i32_e32 v143, 31, v142
	v_lshl_or_b32 v158, s48, 8, v148
	v_lshlrev_b64 v[144:145], 10, v[142:143]
	v_lshl_add_u64 v[144:145], v[144:145], 0, v[158:159]
	v_cndmask_b32_e64 v145, 0, 1, s[58:59]
	v_mul_f32_e32 v126, s18, v126
	v_mul_f32_e32 v127, s19, v127
	v_mul_f32_e32 v124, s16, v124
	v_mul_f32_e32 v125, s17, v125
	v_cmp_ne_u32_e64 s[10:11], 1, v145
	s_andn2_b64 vcc, exec, s[58:59]
	s_mov_b64 s[12:13], -1
	s_cbranch_vccnz .LBB0_608
	v_lshlrev_b32_e32 v145, 2, v144
	s_mov_b64 s[12:13], 0
	buffer_store_dwordx4 v[124:127], v145, s[28:31], 0 offen sc1

.LBB0_610:
	v_or_b32_e32 v145, 16, v144
	v_mul_f32_e32 v122, s18, v122
	v_mul_f32_e32 v123, s19, v123
	v_mul_f32_e32 v120, s16, v120
	v_mul_f32_e32 v121, s17, v121
	s_and_b64 vcc, exec, s[10:11]
	s_mov_b64 s[12:13], -1
	s_cbranch_vccnz .LBB0_612
	v_lshlrev_b32_e32 v150, 2, v145
	s_mov_b64 s[12:13], 0
	buffer_store_dwordx4 v[120:123], v150, s[28:31], 0 offen sc1

.LBB0_614:
	v_or_b32_e32 v145, 0x80, v144
	v_mul_f32_e32 v118, s18, v118
	v_mul_f32_e32 v119, s19, v119
	v_mul_f32_e32 v116, s16, v116
	v_mul_f32_e32 v117, s17, v117
	s_and_b64 vcc, exec, s[10:11]
	s_mov_b64 s[12:13], -1
	s_cbranch_vccnz .LBB0_616
	v_lshlrev_b32_e32 v150, 2, v145
	s_mov_b64 s[12:13], 0
	buffer_store_dwordx4 v[116:119], v150, s[28:31], 0 offen sc1

.LBB0_618:
	v_or_b32_e32 v144, 0x90, v144
	v_mul_f32_e32 v114, s18, v114
	v_mul_f32_e32 v115, s19, v115
	v_mul_f32_e32 v112, s16, v112
	v_mul_f32_e32 v113, s17, v113
	s_and_b64 vcc, exec, s[10:11]
	s_mov_b64 s[12:13], -1
	s_cbranch_vccnz .LBB0_620
	v_lshlrev_b32_e32 v145, 2, v144
	s_mov_b64 s[12:13], 0
	buffer_store_dwordx4 v[112:115], v145, s[28:31], 0 offen sc1

.LBB0_626:
	v_or_b32_e32 v112, 16, v142
	s_waitcnt lgkmcnt(0)
	v_ashrrev_i32_e32 v113, 31, v112
	v_lshlrev_b64 v[114:115], 10, v[112:113]
	v_lshl_add_u64 v[114:115], v[114:115], 0, v[158:159]
	v_mul_f32_e32 v110, s18, v110
	v_mul_f32_e32 v111, s19, v111
	v_mul_f32_e32 v108, s16, v108
	v_mul_f32_e32 v109, s17, v109
	s_and_b64 vcc, exec, s[10:11]
	s_mov_b64 s[72:73], -1
	s_cbranch_vccnz .LBB0_628
	v_lshlrev_b32_e32 v115, 2, v114
	s_mov_b64 s[72:73], 0
	buffer_store_dwordx4 v[108:111], v115, s[28:31], 0 offen sc1

.LBB0_630:
	v_or_b32_e32 v115, 16, v114
	v_mul_f32_e32 v106, s18, v106
	v_mul_f32_e32 v107, s19, v107
	v_mul_f32_e32 v104, s16, v104
	v_mul_f32_e32 v105, s17, v105
	s_and_b64 vcc, exec, s[10:11]
	s_mov_b64 s[72:73], -1
	s_cbranch_vccnz .LBB0_632
	v_lshlrev_b32_e32 v116, 2, v115
	s_mov_b64 s[72:73], 0
	buffer_store_dwordx4 v[104:107], v116, s[28:31], 0 offen sc1

.LBB0_634:
	v_or_b32_e32 v115, 0x80, v114
	v_mul_f32_e32 v102, s18, v102
	v_mul_f32_e32 v103, s19, v103
	v_mul_f32_e32 v100, s16, v100
	v_mul_f32_e32 v101, s17, v101
	s_and_b64 vcc, exec, s[10:11]
	s_mov_b64 s[72:73], -1
	s_cbranch_vccnz .LBB0_636
	v_lshlrev_b32_e32 v116, 2, v115
	s_mov_b64 s[72:73], 0
	buffer_store_dwordx4 v[100:103], v116, s[28:31], 0 offen sc1

.LBB0_638:
	v_or_b32_e32 v114, 0x90, v114
	v_mul_f32_e32 v98, s18, v98
	v_mul_f32_e32 v99, s19, v99
	v_mul_f32_e32 v96, s16, v96
	v_mul_f32_e32 v97, s17, v97
	s_and_b64 vcc, exec, s[10:11]
	s_mov_b64 s[72:73], -1
	s_cbranch_vccnz .LBB0_641
	v_lshlrev_b32_e32 v115, 2, v114
	buffer_store_dwordx4 v[96:99], v115, s[28:31], 0 offen sc1
	s_cbranch_execz .LBB0_642

.LBB0_646:
	v_or_b32_e32 v96, 32, v142
	s_waitcnt lgkmcnt(0)
	v_ashrrev_i32_e32 v97, 31, v96
	v_lshlrev_b64 v[98:99], 10, v[96:97]
	v_lshl_add_u64 v[98:99], v[98:99], 0, v[158:159]
	v_mul_f32_e32 v94, s18, v94
	v_mul_f32_e32 v95, s19, v95
	v_mul_f32_e32 v92, s16, v92
	v_mul_f32_e32 v93, s17, v93
	s_and_b64 vcc, exec, s[10:11]
	s_mov_b64 s[72:73], -1
	s_cbranch_vccnz .LBB0_648
	v_lshlrev_b32_e32 v99, 2, v98
	s_mov_b64 s[72:73], 0
	buffer_store_dwordx4 v[92:95], v99, s[28:31], 0 offen sc1

.LBB0_650:
	v_or_b32_e32 v99, 16, v98
	v_mul_f32_e32 v90, s18, v90
	v_mul_f32_e32 v91, s19, v91
	v_mul_f32_e32 v88, s16, v88
	v_mul_f32_e32 v89, s17, v89
	s_and_b64 vcc, exec, s[10:11]
	s_mov_b64 s[72:73], -1
	s_cbranch_vccnz .LBB0_652
	v_lshlrev_b32_e32 v100, 2, v99
	s_mov_b64 s[72:73], 0
	buffer_store_dwordx4 v[88:91], v100, s[28:31], 0 offen sc1

.LBB0_654:
	v_or_b32_e32 v99, 0x80, v98
	v_mul_f32_e32 v86, s18, v86
	v_mul_f32_e32 v87, s19, v87
	v_mul_f32_e32 v84, s16, v84
	v_mul_f32_e32 v85, s17, v85
	s_and_b64 vcc, exec, s[10:11]
	s_mov_b64 s[72:73], -1
	s_cbranch_vccnz .LBB0_656
	v_lshlrev_b32_e32 v100, 2, v99
	s_mov_b64 s[72:73], 0
	buffer_store_dwordx4 v[84:87], v100, s[28:31], 0 offen sc1

.LBB0_658:
	v_or_b32_e32 v98, 0x90, v98
	v_mul_f32_e32 v82, s18, v82
	v_mul_f32_e32 v83, s19, v83
	v_mul_f32_e32 v80, s16, v80
	v_mul_f32_e32 v81, s17, v81
	s_and_b64 vcc, exec, s[10:11]
	s_mov_b64 s[72:73], -1
	s_cbranch_vccnz .LBB0_661
	v_lshlrev_b32_e32 v99, 2, v98
	buffer_store_dwordx4 v[80:83], v99, s[28:31], 0 offen sc1
	s_cbranch_execz .LBB0_662

.LBB0_666:
	v_or_b32_e32 v80, 48, v142
	s_waitcnt lgkmcnt(0)
	v_ashrrev_i32_e32 v81, 31, v80
	v_lshlrev_b64 v[82:83], 10, v[80:81]
	v_lshl_add_u64 v[82:83], v[82:83], 0, v[158:159]
	v_mul_f32_e32 v78, s18, v78
	v_mul_f32_e32 v79, s19, v79
	v_mul_f32_e32 v76, s16, v76
	v_mul_f32_e32 v77, s17, v77
	s_and_b64 vcc, exec, s[10:11]
	s_mov_b64 s[72:73], -1
	s_cbranch_vccnz .LBB0_668
	v_lshlrev_b32_e32 v83, 2, v82
	s_mov_b64 s[72:73], 0
	buffer_store_dwordx4 v[76:79], v83, s[28:31], 0 offen sc1

.LBB0_670:
	v_or_b32_e32 v83, 16, v82
	v_mul_f32_e32 v74, s18, v74
	v_mul_f32_e32 v75, s19, v75
	v_mul_f32_e32 v72, s16, v72
	v_mul_f32_e32 v73, s17, v73
	s_and_b64 vcc, exec, s[10:11]
	s_mov_b64 s[72:73], -1
	s_cbranch_vccnz .LBB0_672
	v_lshlrev_b32_e32 v84, 2, v83
	s_mov_b64 s[72:73], 0
	buffer_store_dwordx4 v[72:75], v84, s[28:31], 0 offen sc1

.LBB0_674:
	v_or_b32_e32 v83, 0x80, v82
	v_mul_f32_e32 v70, s18, v70
	v_mul_f32_e32 v71, s19, v71
	v_mul_f32_e32 v68, s16, v68
	v_mul_f32_e32 v69, s17, v69
	s_and_b64 vcc, exec, s[10:11]
	s_mov_b64 s[72:73], -1
	s_cbranch_vccnz .LBB0_676
	v_lshlrev_b32_e32 v84, 2, v83
	s_mov_b64 s[72:73], 0
	buffer_store_dwordx4 v[68:71], v84, s[28:31], 0 offen sc1

.LBB0_678:
	v_or_b32_e32 v82, 0x90, v82
	v_mul_f32_e32 v66, s18, v66
	v_mul_f32_e32 v67, s19, v67
	v_mul_f32_e32 v64, s16, v64
	v_mul_f32_e32 v65, s17, v65
	s_and_b64 vcc, exec, s[10:11]
	s_mov_b64 s[72:73], -1
	s_cbranch_vccnz .LBB0_681
	v_lshlrev_b32_e32 v83, 2, v82
	buffer_store_dwordx4 v[64:67], v83, s[28:31], 0 offen sc1
	s_cbranch_execz .LBB0_682

.LBB0_686:
	v_add_u32_e32 v64, 0x80, v142
	s_waitcnt lgkmcnt(0)
	v_ashrrev_i32_e32 v65, 31, v64
	v_lshlrev_b64 v[66:67], 10, v[64:65]
	v_lshl_add_u64 v[66:67], v[66:67], 0, v[158:159]
	v_mul_f32_e32 v62, s18, v62
	v_mul_f32_e32 v63, s19, v63
	v_mul_f32_e32 v60, s16, v60
	v_mul_f32_e32 v61, s17, v61
	s_and_b64 vcc, exec, s[10:11]
	s_mov_b64 s[72:73], -1
	s_cbranch_vccnz .LBB0_688
	v_lshlrev_b32_e32 v67, 2, v66
	s_mov_b64 s[72:73], 0
	buffer_store_dwordx4 v[60:63], v67, s[28:31], 0 offen sc1

.LBB0_690:
	v_or_b32_e32 v67, 16, v66
	v_mul_f32_e32 v58, s18, v58
	v_mul_f32_e32 v59, s19, v59
	v_mul_f32_e32 v56, s16, v56
	v_mul_f32_e32 v57, s17, v57
	s_and_b64 vcc, exec, s[10:11]
	s_mov_b64 s[72:73], -1
	s_cbranch_vccnz .LBB0_692
	v_lshlrev_b32_e32 v68, 2, v67
	s_mov_b64 s[72:73], 0
	buffer_store_dwordx4 v[56:59], v68, s[28:31], 0 offen sc1

.LBB0_694:
	v_or_b32_e32 v67, 0x80, v66
	v_mul_f32_e32 v54, s18, v54
	v_mul_f32_e32 v55, s19, v55
	v_mul_f32_e32 v52, s16, v52
	v_mul_f32_e32 v53, s17, v53
	s_and_b64 vcc, exec, s[10:11]
	s_mov_b64 s[72:73], -1
	s_cbranch_vccnz .LBB0_696
	v_lshlrev_b32_e32 v68, 2, v67
	s_mov_b64 s[72:73], 0
	buffer_store_dwordx4 v[52:55], v68, s[28:31], 0 offen sc1

.LBB0_698:
	v_or_b32_e32 v66, 0x90, v66
	v_mul_f32_e32 v50, s18, v50
	v_mul_f32_e32 v51, s19, v51
	v_mul_f32_e32 v48, s16, v48
	v_mul_f32_e32 v49, s17, v49
	s_and_b64 vcc, exec, s[10:11]
	s_mov_b64 s[72:73], -1
	s_cbranch_vccnz .LBB0_701
	v_lshlrev_b32_e32 v67, 2, v66
	buffer_store_dwordx4 v[48:51], v67, s[28:31], 0 offen sc1
	s_cbranch_execz .LBB0_702

.LBB0_706:
	v_add_u32_e32 v48, 0x90, v142
	s_waitcnt lgkmcnt(0)
	v_ashrrev_i32_e32 v49, 31, v48
	v_lshlrev_b64 v[50:51], 10, v[48:49]
	v_lshl_add_u64 v[50:51], v[50:51], 0, v[158:159]
	v_mul_f32_e32 v46, s18, v46
	v_mul_f32_e32 v47, s19, v47
	v_mul_f32_e32 v44, s16, v44
	v_mul_f32_e32 v45, s17, v45
	s_and_b64 vcc, exec, s[10:11]
	s_mov_b64 s[72:73], -1
	s_cbranch_vccnz .LBB0_708
	v_lshlrev_b32_e32 v51, 2, v50
	s_mov_b64 s[72:73], 0
	buffer_store_dwordx4 v[44:47], v51, s[28:31], 0 offen sc1

.LBB0_710:
	v_or_b32_e32 v51, 16, v50
	v_mul_f32_e32 v42, s18, v42
	v_mul_f32_e32 v43, s19, v43
	v_mul_f32_e32 v40, s16, v40
	v_mul_f32_e32 v41, s17, v41
	s_and_b64 vcc, exec, s[10:11]
	s_mov_b64 s[72:73], -1
	s_cbranch_vccnz .LBB0_712
	v_lshlrev_b32_e32 v52, 2, v51
	s_mov_b64 s[72:73], 0
	buffer_store_dwordx4 v[40:43], v52, s[28:31], 0 offen sc1

.LBB0_714:
	v_or_b32_e32 v51, 0x80, v50
	v_mul_f32_e32 v38, s18, v38
	v_mul_f32_e32 v39, s19, v39
	v_mul_f32_e32 v36, s16, v36
	v_mul_f32_e32 v37, s17, v37
	s_and_b64 vcc, exec, s[10:11]
	s_mov_b64 s[72:73], -1
	s_cbranch_vccnz .LBB0_716
	v_lshlrev_b32_e32 v52, 2, v51
	s_mov_b64 s[72:73], 0
	buffer_store_dwordx4 v[36:39], v52, s[28:31], 0 offen sc1

.LBB0_718:
	v_or_b32_e32 v50, 0x90, v50
	v_mul_f32_e32 v34, s18, v34
	v_mul_f32_e32 v35, s19, v35
	v_mul_f32_e32 v32, s16, v32
	v_mul_f32_e32 v33, s17, v33
	s_and_b64 vcc, exec, s[10:11]
	s_mov_b64 s[72:73], -1
	s_cbranch_vccnz .LBB0_721
	v_lshlrev_b32_e32 v51, 2, v50
	buffer_store_dwordx4 v[32:35], v51, s[28:31], 0 offen sc1
	s_cbranch_execz .LBB0_722

.LBB0_726:
	v_add_u32_e32 v32, 0xa0, v142
	s_waitcnt lgkmcnt(0)
	v_ashrrev_i32_e32 v33, 31, v32
	v_lshlrev_b64 v[34:35], 10, v[32:33]
	v_lshl_add_u64 v[34:35], v[34:35], 0, v[158:159]
	v_mul_f32_e32 v30, s18, v30
	v_mul_f32_e32 v31, s19, v31
	v_mul_f32_e32 v28, s16, v28
	v_mul_f32_e32 v29, s17, v29
	s_and_b64 vcc, exec, s[10:11]
	s_mov_b64 s[72:73], -1
	s_cbranch_vccnz .LBB0_728
	v_lshlrev_b32_e32 v35, 2, v34
	s_mov_b64 s[72:73], 0
	buffer_store_dwordx4 v[28:31], v35, s[28:31], 0 offen sc1

.LBB0_730:
	v_or_b32_e32 v35, 16, v34
	v_mul_f32_e32 v26, s18, v26
	v_mul_f32_e32 v27, s19, v27
	v_mul_f32_e32 v24, s16, v24
	v_mul_f32_e32 v25, s17, v25
	s_and_b64 vcc, exec, s[10:11]
	s_mov_b64 s[72:73], -1
	s_cbranch_vccnz .LBB0_732
	v_lshlrev_b32_e32 v36, 2, v35
	s_mov_b64 s[72:73], 0
	buffer_store_dwordx4 v[24:27], v36, s[28:31], 0 offen sc1

.LBB0_734:
	v_or_b32_e32 v35, 0x80, v34
	v_mul_f32_e32 v22, s18, v22
	v_mul_f32_e32 v23, s19, v23
	v_mul_f32_e32 v20, s16, v20
	v_mul_f32_e32 v21, s17, v21
	s_and_b64 vcc, exec, s[10:11]
	s_mov_b64 s[72:73], -1
	s_cbranch_vccnz .LBB0_736
	v_lshlrev_b32_e32 v36, 2, v35
	s_mov_b64 s[72:73], 0
	buffer_store_dwordx4 v[20:23], v36, s[28:31], 0 offen sc1

.LBB0_738:
	v_or_b32_e32 v34, 0x90, v34
	v_mul_f32_e32 v18, s18, v18
	v_mul_f32_e32 v19, s19, v19
	v_mul_f32_e32 v16, s16, v16
	v_mul_f32_e32 v17, s17, v17
	s_and_b64 vcc, exec, s[10:11]
	s_mov_b64 s[72:73], -1
	s_cbranch_vccnz .LBB0_741
	v_lshlrev_b32_e32 v35, 2, v34
	buffer_store_dwordx4 v[16:19], v35, s[28:31], 0 offen sc1
	s_cbranch_execz .LBB0_742

.LBB0_746:
	v_add_u32_e32 v16, 0xb0, v142
	s_waitcnt lgkmcnt(0)
	v_ashrrev_i32_e32 v17, 31, v16
	v_lshlrev_b64 v[18:19], 10, v[16:17]
	v_lshl_add_u64 v[18:19], v[18:19], 0, v[158:159]
	v_mul_f32_e32 v14, s18, v14
	v_mul_f32_e32 v15, s19, v15
	v_mul_f32_e32 v12, s16, v12
	v_mul_f32_e32 v13, s17, v13
	s_and_b64 vcc, exec, s[10:11]
	s_mov_b64 s[72:73], -1
	s_cbranch_vccnz .LBB0_748
	v_lshlrev_b32_e32 v19, 2, v18
	s_mov_b64 s[72:73], 0
	buffer_store_dwordx4 v[12:15], v19, s[28:31], 0 offen sc1

.LBB0_750:
	v_or_b32_e32 v19, 16, v18
	v_mul_f32_e32 v10, s18, v10
	v_mul_f32_e32 v11, s19, v11
	v_mul_f32_e32 v8, s16, v8
	v_mul_f32_e32 v9, s17, v9
	s_and_b64 vcc, exec, s[10:11]
	s_mov_b64 s[72:73], -1
	s_cbranch_vccnz .LBB0_752
	v_lshlrev_b32_e32 v20, 2, v19
	s_mov_b64 s[72:73], 0
	buffer_store_dwordx4 v[8:11], v20, s[28:31], 0 offen sc1

.LBB0_754:
	v_or_b32_e32 v19, 0x80, v18
	v_mul_f32_e32 v6, s18, v6
	v_mul_f32_e32 v7, s19, v7
	v_mul_f32_e32 v4, s16, v4
	v_mul_f32_e32 v5, s17, v5
	s_and_b64 vcc, exec, s[10:11]
	s_mov_b64 s[72:73], -1
	s_cbranch_vccnz .LBB0_756
	v_lshlrev_b32_e32 v20, 2, v19
	s_mov_b64 s[72:73], 0
	buffer_store_dwordx4 v[4:7], v20, s[28:31], 0 offen sc1

.LBB0_758:
	v_or_b32_e32 v18, 0x90, v18
	v_mul_f32_e32 v2, s18, v2
	v_mul_f32_e32 v3, s19, v3
	v_mul_f32_e32 v0, s16, v0
	v_mul_f32_e32 v1, s17, v1
	s_and_b64 vcc, exec, s[10:11]
	s_mov_b64 s[10:11], -1
	s_cbranch_vccnz .LBB0_762
	v_lshlrev_b32_e32 v19, 2, v18
	buffer_store_dwordx4 v[0:3], v19, s[28:31], 0 offen sc1
	s_cbranch_execz .LBB0_763

.LBB0_767:
	v_lshl_add_u32 v0, s51, 8, v146
	v_lshl_or_b32 v2, s23, 8, v148
	s_waitcnt lgkmcnt(0)
	v_ashrrev_i32_e32 v1, 31, v0
	v_ashrrev_i32_e32 v3, 31, v2
	v_lshlrev_b64 v[4:5], 11, v[0:1]
	v_lshl_add_u64 v[4:5], s[96:97], 0, v[4:5]
	v_lshlrev_b64 v[2:3], 1, v[2:3]
	v_lshl_add_u64 v[4:5], v[4:5], 0, v[2:3]
	v_or_b32_e32 v6, 16, v0
	global_load_dwordx2 v[34:35], v[4:5], off
	global_load_dwordx2 v[36:37], v[4:5], off offset:32
	global_load_dwordx2 v[38:39], v[4:5], off offset:256
	v_ashrrev_i32_e32 v7, 31, v6
	v_lshlrev_b64 v[6:7], 11, v[6:7]
	global_load_dwordx2 v[40:41], v[4:5], off offset:288
	v_lshl_add_u64 v[6:7], s[96:97], 0, v[6:7]
	v_lshl_add_u64 v[6:7], v[6:7], 0, v[2:3]
	global_load_dwordx2 v[42:43], v[6:7], off
	global_load_dwordx2 v[44:45], v[6:7], off offset:32
	global_load_dwordx2 v[46:47], v[6:7], off offset:256
	v_or_b32_e32 v8, 32, v0
	v_ashrrev_i32_e32 v9, 31, v8
	v_lshlrev_b64 v[8:9], 11, v[8:9]
	v_lshl_add_u64 v[8:9], s[96:97], 0, v[8:9]
	global_load_dwordx2 v[48:49], v[6:7], off offset:288
	v_lshl_add_u64 v[8:9], v[8:9], 0, v[2:3]
	global_load_dwordx2 v[52:53], v[8:9], off
	global_load_dwordx2 v[56:57], v[8:9], off offset:32
	v_or_b32_e32 v0, 48, v0
	s_mov_b32 s2, 0x40000
	v_ashrrev_i32_e32 v1, 31, v0
	v_add_co_u32_e32 v10, vcc, s2, v4
	v_lshlrev_b64 v[0:1], 11, v[0:1]
	s_nop 0
	v_addc_co_u32_e32 v11, vcc, 0, v5, vcc
	s_mov_b32 s2, 0x48000
	v_lshl_add_u64 v[0:1], s[96:97], 0, v[0:1]
	s_mov_b64 s[8:9], 0x40000
	v_add_co_u32_e32 v6, vcc, s2, v4
	v_lshl_add_u64 v[0:1], v[0:1], 0, v[2:3]
	v_lshl_add_u64 v[2:3], v[4:5], 0, s[8:9]
	s_mov_b64 s[8:9], 0x48000
	v_addc_co_u32_e32 v7, vcc, 0, v5, vcc
	s_mov_b32 s2, 0x50000
	v_lshl_add_u64 v[12:13], v[4:5], 0, s[8:9]
	s_mov_b64 s[8:9], 0x50000
	v_add_co_u32_e32 v14, vcc, s2, v4
	v_lshl_add_u64 v[50:51], v[4:5], 0, s[8:9]
	s_nop 0
	v_addc_co_u32_e32 v15, vcc, 0, v5, vcc
	s_mov_b64 s[8:9], 0x58000
	s_mov_b32 s2, 0x58000
	v_lshl_add_u64 v[54:55], v[4:5], 0, s[8:9]
	v_add_co_u32_e32 v4, vcc, s2, v4
	s_mov_b64 s[8:9], 0
	s_nop 0
	v_addc_co_u32_e32 v5, vcc, 0, v5, vcc
	global_load_dwordx2 v[58:59], v[8:9], off offset:256
	global_load_dwordx2 v[60:61], v[8:9], off offset:288
	global_load_dwordx2 v[62:63], v[0:1], off
	global_load_dwordx2 v[64:65], v[0:1], off offset:32
	global_load_dwordx2 v[66:67], v[0:1], off offset:256
	global_load_dwordx2 v[32:33], v[0:1], off offset:288
	global_load_dwordx2 v[30:31], v[10:11], off
	global_load_dwordx2 v[28:29], v[2:3], off offset:32
	global_load_dwordx2 v[26:27], v[2:3], off offset:256
	global_load_dwordx2 v[24:25], v[2:3], off offset:288
	global_load_dwordx2 v[22:23], v[6:7], off
	global_load_dwordx2 v[20:21], v[12:13], off offset:32
	global_load_dwordx2 v[18:19], v[12:13], off offset:256
	global_load_dwordx2 v[16:17], v[12:13], off offset:288
	s_nop 0
	global_load_dwordx2 v[14:15], v[14:15], off
	s_nop 0
	global_load_dwordx2 v[12:13], v[50:51], off offset:32
	global_load_dwordx2 v[10:11], v[50:51], off offset:256
	global_load_dwordx2 v[8:9], v[50:51], off offset:288
	global_load_dwordx2 v[6:7], v[4:5], off
	s_nop 0
	global_load_dwordx2 v[4:5], v[54:55], off offset:32
	global_load_dwordx2 v[0:1], v[54:55], off offset:256
	global_load_dwordx2 v[2:3], v[54:55], off offset:288
	s_waitcnt vmcnt(0)
	v_lshlrev_b32_e32 v50, 16, v34
	v_and_b32_e32 v51, 0xffff0000, v34
	v_lshlrev_b32_e32 v34, 16, v35
	v_and_b32_e32 v35, 0xffff0000, v35
	v_mul_f32_e32 v126, v136, v34
	v_mul_f32_e32 v127, v137, v35
	v_lshlrev_b32_e32 v34, 16, v38
	v_and_b32_e32 v35, 0xffff0000, v38
	v_mul_f32_e32 v116, v136, v34
	v_mul_f32_e32 v117, v137, v35
	v_lshlrev_b32_e32 v34, 16, v39
	v_and_b32_e32 v35, 0xffff0000, v39
	v_mul_f32_e32 v118, v136, v34
	v_mul_f32_e32 v119, v137, v35
	v_lshlrev_b32_e32 v34, 16, v40
	v_and_b32_e32 v35, 0xffff0000, v40
	v_mul_f32_e32 v112, v136, v34
	v_mul_f32_e32 v113, v137, v35
	v_lshlrev_b32_e32 v34, 16, v41
	v_and_b32_e32 v35, 0xffff0000, v41
	v_mul_f32_e32 v114, v136, v34
	v_mul_f32_e32 v115, v137, v35
	v_lshlrev_b32_e32 v34, 16, v42
	v_and_b32_e32 v35, 0xffff0000, v42
	v_mul_f32_e32 v108, v136, v34
	v_mul_f32_e32 v109, v137, v35
	v_lshlrev_b32_e32 v34, 16, v43
	v_and_b32_e32 v35, 0xffff0000, v43
	v_mul_f32_e32 v110, v136, v34
	v_mul_f32_e32 v111, v137, v35
	v_lshlrev_b32_e32 v34, 16, v44
	v_and_b32_e32 v35, 0xffff0000, v44
	v_mul_f32_e32 v104, v136, v34
	v_mul_f32_e32 v105, v137, v35
	v_lshlrev_b32_e32 v34, 16, v45
	v_and_b32_e32 v35, 0xffff0000, v45
	v_mul_f32_e32 v106, v136, v34
	v_mul_f32_e32 v107, v137, v35
	v_lshlrev_b32_e32 v34, 16, v46
	v_and_b32_e32 v35, 0xffff0000, v46
	v_mul_f32_e32 v100, v136, v34
	v_mul_f32_e32 v101, v137, v35
	v_lshlrev_b32_e32 v34, 16, v47
	v_and_b32_e32 v35, 0xffff0000, v47
	v_mul_f32_e32 v102, v136, v34
	v_mul_f32_e32 v103, v137, v35
	v_lshlrev_b32_e32 v34, 16, v48
	v_and_b32_e32 v35, 0xffff0000, v48
	v_mul_f32_e32 v96, v136, v34
	v_mul_f32_e32 v97, v137, v35
	v_lshlrev_b32_e32 v34, 16, v49
	v_and_b32_e32 v35, 0xffff0000, v49
	v_mul_f32_e32 v98, v136, v34
	v_mul_f32_e32 v99, v137, v35
	v_lshlrev_b32_e32 v34, 16, v52
	v_and_b32_e32 v35, 0xffff0000, v52
	v_mul_f32_e32 v92, v136, v34
	v_mul_f32_e32 v93, v137, v35
	v_lshlrev_b32_e32 v34, 16, v53
	v_and_b32_e32 v35, 0xffff0000, v53
	v_mul_f32_e32 v94, v136, v34
	v_mul_f32_e32 v95, v137, v35
	v_lshlrev_b32_e32 v34, 16, v56
	v_and_b32_e32 v35, 0xffff0000, v56
	v_mul_f32_e32 v88, v136, v34
	v_mul_f32_e32 v89, v137, v35
	v_lshlrev_b32_e32 v34, 16, v57
	v_and_b32_e32 v35, 0xffff0000, v57
	v_mul_f32_e32 v90, v136, v34
	v_mul_f32_e32 v91, v137, v35
	v_lshlrev_b32_e32 v34, 16, v58
	v_and_b32_e32 v35, 0xffff0000, v58
	v_mul_f32_e32 v84, v136, v34
	v_mul_f32_e32 v85, v137, v35
	v_lshlrev_b32_e32 v34, 16, v59
	v_and_b32_e32 v35, 0xffff0000, v59
	v_mul_f32_e32 v86, v136, v34
	v_mul_f32_e32 v87, v137, v35
	v_lshlrev_b32_e32 v34, 16, v60
	v_and_b32_e32 v35, 0xffff0000, v60
	v_mul_f32_e32 v80, v136, v34
	v_mul_f32_e32 v81, v137, v35
	v_lshlrev_b32_e32 v34, 16, v61
	v_and_b32_e32 v35, 0xffff0000, v61
	v_mul_f32_e32 v82, v136, v34
	v_mul_f32_e32 v83, v137, v35
	v_lshlrev_b32_e32 v34, 16, v62
	v_and_b32_e32 v35, 0xffff0000, v62
	v_mul_f32_e32 v76, v136, v34
	v_mul_f32_e32 v77, v137, v35
	v_lshlrev_b32_e32 v34, 16, v63
	v_and_b32_e32 v35, 0xffff0000, v63
	v_mul_f32_e32 v78, v136, v34
	v_mul_f32_e32 v79, v137, v35
	v_lshlrev_b32_e32 v34, 16, v64
	v_and_b32_e32 v35, 0xffff0000, v64
	v_mul_f32_e32 v72, v136, v34
	v_mul_f32_e32 v73, v137, v35
	v_lshlrev_b32_e32 v34, 16, v65
	v_and_b32_e32 v35, 0xffff0000, v65
	v_mul_f32_e32 v74, v136, v34
	v_mul_f32_e32 v75, v137, v35
	v_lshlrev_b32_e32 v34, 16, v66
	v_and_b32_e32 v35, 0xffff0000, v66
	v_mul_f32_e32 v68, v136, v34
	v_mul_f32_e32 v69, v137, v35
	v_lshlrev_b32_e32 v34, 16, v67
	v_and_b32_e32 v35, 0xffff0000, v67
	v_mul_f32_e32 v70, v136, v34
	v_mul_f32_e32 v71, v137, v35
	v_lshlrev_b32_e32 v34, 16, v32
	v_and_b32_e32 v35, 0xffff0000, v32
	v_lshlrev_b32_e32 v32, 16, v33
	v_and_b32_e32 v33, 0xffff0000, v33
	v_mul_f32_e32 v66, v136, v32
	v_mul_f32_e32 v67, v137, v33
	v_lshlrev_b32_e32 v32, 16, v30
	v_and_b32_e32 v33, 0xffff0000, v30
	v_lshlrev_b32_e32 v30, 16, v31
	v_and_b32_e32 v31, 0xffff0000, v31
	v_mul_f32_e32 v62, v136, v30
	v_mul_f32_e32 v63, v137, v31
	v_lshlrev_b32_e32 v30, 16, v28
	v_and_b32_e32 v31, 0xffff0000, v28
	v_lshlrev_b32_e32 v28, 16, v29
	v_and_b32_e32 v29, 0xffff0000, v29
	v_lshlrev_b32_e32 v54, 16, v36
	v_and_b32_e32 v55, 0xffff0000, v36
	v_mul_f32_e32 v58, v136, v28
	v_mul_f32_e32 v59, v137, v29
	v_lshlrev_b32_e32 v28, 16, v26
	v_and_b32_e32 v29, 0xffff0000, v26
	v_lshlrev_b32_e32 v26, 16, v27
	v_and_b32_e32 v27, 0xffff0000, v27
	v_mul_f32_e32 v120, v136, v54
	v_mul_f32_e32 v121, v137, v55
	v_mul_f32_e32 v54, v136, v26
	v_mul_f32_e32 v55, v137, v27
	v_lshlrev_b32_e32 v26, 16, v24
	v_and_b32_e32 v27, 0xffff0000, v24
	v_lshlrev_b32_e32 v24, 16, v25
	v_and_b32_e32 v25, 0xffff0000, v25
	v_mul_f32_e32 v124, v136, v50
	v_mul_f32_e32 v125, v137, v51
	v_mul_f32_e32 v50, v136, v24
	v_mul_f32_e32 v51, v137, v25
	v_lshlrev_b32_e32 v24, 16, v22
	v_and_b32_e32 v25, 0xffff0000, v22
	v_lshlrev_b32_e32 v22, 16, v23
	v_and_b32_e32 v23, 0xffff0000, v23
	v_mul_f32_e32 v46, v136, v22
	v_mul_f32_e32 v47, v137, v23
	v_lshlrev_b32_e32 v22, 16, v20
	v_and_b32_e32 v23, 0xffff0000, v20
	v_lshlrev_b32_e32 v20, 16, v21
	v_and_b32_e32 v21, 0xffff0000, v21
	v_mul_f32_e32 v42, v136, v20
	v_mul_f32_e32 v43, v137, v21
	v_lshlrev_b32_e32 v20, 16, v18
	v_and_b32_e32 v21, 0xffff0000, v18
	v_lshlrev_b32_e32 v18, 16, v19
	v_and_b32_e32 v19, 0xffff0000, v19
	v_mul_f32_e32 v38, v136, v18
	v_mul_f32_e32 v39, v137, v19
	v_lshlrev_b32_e32 v18, 16, v16
	v_and_b32_e32 v19, 0xffff0000, v16
	v_lshlrev_b32_e32 v16, 16, v17
	v_and_b32_e32 v17, 0xffff0000, v17
	v_mul_f32_e32 v64, v136, v34
	v_mul_f32_e32 v65, v137, v35
	v_mul_f32_e32 v34, v136, v16
	v_mul_f32_e32 v35, v137, v17
	v_lshlrev_b32_e32 v16, 16, v14
	v_and_b32_e32 v17, 0xffff0000, v14
	v_lshlrev_b32_e32 v14, 16, v15
	v_and_b32_e32 v15, 0xffff0000, v15
	v_mul_f32_e32 v56, v136, v30
	v_mul_f32_e32 v57, v137, v31
	v_mul_f32_e32 v30, v136, v14
	v_mul_f32_e32 v31, v137, v15
	v_lshlrev_b32_e32 v14, 16, v12
	v_and_b32_e32 v15, 0xffff0000, v12
	v_lshlrev_b32_e32 v12, 16, v13
	v_and_b32_e32 v13, 0xffff0000, v13
	v_mul_f32_e32 v48, v136, v26
	v_mul_f32_e32 v49, v137, v27
	v_mul_f32_e32 v26, v136, v12
	v_mul_f32_e32 v27, v137, v13
	v_lshlrev_b32_e32 v12, 16, v10
	v_and_b32_e32 v13, 0xffff0000, v10
	v_lshlrev_b32_e32 v10, 16, v11
	v_and_b32_e32 v11, 0xffff0000, v11
	v_mul_f32_e32 v40, v136, v22
	v_mul_f32_e32 v41, v137, v23
	v_mul_f32_e32 v22, v136, v10
	v_mul_f32_e32 v23, v137, v11
	v_lshlrev_b32_e32 v10, 16, v8
	v_and_b32_e32 v11, 0xffff0000, v8
	v_lshlrev_b32_e32 v8, 16, v9
	v_and_b32_e32 v9, 0xffff0000, v9
	v_mul_f32_e32 v60, v136, v32
	v_mul_f32_e32 v61, v137, v33
	v_mul_f32_e32 v32, v136, v18
	v_mul_f32_e32 v33, v137, v19
	v_mul_f32_e32 v18, v136, v8
	v_mul_f32_e32 v19, v137, v9
	v_lshlrev_b32_e32 v8, 16, v6
	v_and_b32_e32 v9, 0xffff0000, v6
	v_lshlrev_b32_e32 v6, 16, v7
	v_and_b32_e32 v7, 0xffff0000, v7
	v_mul_f32_e32 v44, v136, v24
	v_mul_f32_e32 v45, v137, v25
	v_mul_f32_e32 v24, v136, v14
	v_mul_f32_e32 v25, v137, v15
	v_mul_f32_e32 v14, v136, v6
	v_mul_f32_e32 v15, v137, v7
	v_lshlrev_b32_e32 v6, 16, v4
	v_and_b32_e32 v7, 0xffff0000, v4
	v_lshlrev_b32_e32 v4, 16, v5
	v_and_b32_e32 v5, 0xffff0000, v5
	v_lshlrev_b32_e32 v36, 16, v37
	v_and_b32_e32 v37, 0xffff0000, v37
	v_mul_f32_e32 v52, v136, v28
	v_mul_f32_e32 v53, v137, v29
	v_mul_f32_e32 v28, v136, v16
	v_mul_f32_e32 v29, v137, v17
	v_mul_f32_e32 v16, v136, v10
	v_mul_f32_e32 v17, v137, v11
	v_mul_f32_e32 v10, v136, v4
	v_mul_f32_e32 v11, v137, v5
	v_lshlrev_b32_e32 v4, 16, v0
	v_and_b32_e32 v5, 0xffff0000, v0
	v_lshlrev_b32_e32 v0, 16, v1
	v_and_b32_e32 v1, 0xffff0000, v1
	v_mul_f32_e32 v122, v136, v36
	v_mul_f32_e32 v123, v137, v37
	v_mul_f32_e32 v36, v136, v20
	v_mul_f32_e32 v37, v137, v21
	v_mul_f32_e32 v20, v136, v12
	v_mul_f32_e32 v21, v137, v13
	v_mul_f32_e32 v12, v136, v8
	v_mul_f32_e32 v13, v137, v9
	v_mul_f32_e32 v8, v136, v6
	v_mul_f32_e32 v9, v137, v7
	v_mul_f32_e32 v6, v136, v0
	v_mul_f32_e32 v7, v137, v1
	v_lshlrev_b32_e32 v0, 16, v2
	v_and_b32_e32 v1, 0xffff0000, v2
	v_lshlrev_b32_e32 v2, 16, v3
	v_and_b32_e32 v3, 0xffff0000, v3
	v_mul_f32_e32 v4, v136, v4
	v_mul_f32_e32 v5, v137, v5
	v_mul_f32_e32 v0, v136, v0
	v_mul_f32_e32 v1, v137, v1
	v_mul_f32_e32 v2, v136, v2
	v_mul_f32_e32 v3, v137, v3
	s_branch .LBB0_593
